# expert weight conversion loops in phase 1 also use non-temporal stores for the converted weights
# speedup vs baseline: 1.0310x; 1.0025x over previous
; #define LAS __attribute__((address_space(3)))
; __device__ __forceinline__ unsigned cvt_pk_bf16(float lo, float hi) { unsigned r; asm("v_cvt_pk_bf16_f32 %0, %1, %2" : "=v"(r) : "v"(lo), "v"(hi)); return r; }
;     ...
;             for (int j = 0; j < 2; ++j) { const int row = (tid >> 4) + 32 * j, c4 = (tid & 15) * 4; LAS float* tp = tile + q * (64 * 65) + row * 65 + c4;
;                 tp[0] = v[q][j][0]; tp[1] = v[q][j][1]; tp[2] = v[q][j][2]; tp[3] = v[q][j][3]; }
;         __syncthreads();
; #pragma unroll
;         for (int q = 0; q < 4; ++q) { const int it = gi * 4 + q;
;             if (it < total) { const int b = it / per, r = it % per, k0 = (r / tn) * 64, n0 = (r % tn) * 64;
;                 const int n = tid >> 3, kc = (tid & 7) * 8;
;                 if (n0 + n < N) { float f[8];
; #pragma unroll
;                     for (int j = 0; j < 8; ++j) f[j] = tile[q * (64 * 65) + (kc + j) * 65 + n];
;                     u32x4 w; w.x = cvt_pk_bf16(f[0], f[1]); w.y = cvt_pk_bf16(f[2], f[3]); w.z = cvt_pk_bf16(f[4], f[5]); w.w = cvt_pk_bf16(f[6], f[7]);
;                     int nd = n0 + n + nshift; if (nd >= N) nd -= N;
;                     *(u32x4*)(dst + (size_t)b * dbs + (size_t)nd * ldd + kofs + k0 + kc) = w; } } }
; __device__ void phase_convert(const Params& p, LAS unsigned char* lds) {
;     ...
;     cvt_job(tile, p.ewg, (bf16_t*)(ws + WS_WG), NE, 1024, FF, 1024, 0, (size_t)1024 * FF, (size_t)FF * 1024, (int)blockIdx.x, (int)gridDim.x);
.Lcv_ewg_nopf:
	s_waitcnt lgkmcnt(0)
	s_barrier
	ds_read2_b32 v[32:33], v88 offset1:65
	ds_read2_b32 v[34:35], v88 offset0:130 offset1:195
	ds_read2_b32 v[36:37], v89 offset0:4 offset1:69
	ds_read2_b32 v[38:39], v89 offset0:134 offset1:199
	ds_read2_b32 v[40:41], v90 offset1:65
	ds_read2_b32 v[42:43], v90 offset0:130 offset1:195
	ds_read2_b32 v[44:45], v91 offset0:4 offset1:69
	ds_read2_b32 v[46:47], v91 offset0:134 offset1:199
	ds_read2_b32 v[48:49], v92 offset1:65
	ds_read2_b32 v[50:51], v92 offset0:130 offset1:195
	ds_read2_b32 v[52:53], v93 offset0:4 offset1:69
	ds_read2_b32 v[54:55], v93 offset0:134 offset1:199
	ds_read2_b32 v[56:57], v94 offset1:65
	ds_read2_b32 v[58:59], v94 offset0:130 offset1:195
	ds_read2_b32 v[60:61], v95 offset0:4 offset1:69
	ds_read2_b32 v[62:63], v95 offset0:134 offset1:199
	s_waitcnt lgkmcnt(12)
	v_cvt_pk_bf16_f32 v64, v32, v33
	v_cvt_pk_bf16_f32 v65, v34, v35
	v_cvt_pk_bf16_f32 v66, v36, v37
	v_cvt_pk_bf16_f32 v67, v38, v39
	global_store_dwordx4 v103, v[64:67], s[8:9] nt
	s_waitcnt lgkmcnt(8)
	v_cvt_pk_bf16_f32 v68, v40, v41
	v_cvt_pk_bf16_f32 v69, v42, v43
	v_cvt_pk_bf16_f32 v70, v44, v45
	v_cvt_pk_bf16_f32 v71, v46, v47
	s_add_u32 s10, s8, 0x20000
	s_addc_u32 s11, s9, 0
	global_store_dwordx4 v103, v[68:71], s[10:11] nt
	s_waitcnt lgkmcnt(4)
	v_cvt_pk_bf16_f32 v72, v48, v49
	v_cvt_pk_bf16_f32 v73, v50, v51
	v_cvt_pk_bf16_f32 v74, v52, v53
	v_cvt_pk_bf16_f32 v75, v54, v55
	s_add_u32 s10, s8, 0x40000
	s_addc_u32 s11, s9, 0
	global_store_dwordx4 v103, v[72:75], s[10:11] nt
	s_waitcnt lgkmcnt(0)
	v_cvt_pk_bf16_f32 v76, v56, v57
	v_cvt_pk_bf16_f32 v77, v58, v59
	v_cvt_pk_bf16_f32 v78, v60, v61
	v_cvt_pk_bf16_f32 v79, v62, v63
	s_add_u32 s10, s8, 0x60000
	s_addc_u32 s11, s9, 0
	global_store_dwordx4 v103, v[76:79], s[10:11] nt
	s_barrier
	s_mov_b32 s20, s21
	s_cmpk_lt_i32 s20, 0x800
	s_cbranch_scc1 .Lcv_ewg_loop

; #define LAS __attribute__((address_space(3)))
; __device__ __forceinline__ unsigned cvt_pk_bf16(float lo, float hi) { unsigned r; asm("v_cvt_pk_bf16_f32 %0, %1, %2" : "=v"(r) : "v"(lo), "v"(hi)); return r; }
;     ...
;             for (int j = 0; j < 2; ++j) { const int row = (tid >> 4) + 32 * j, c4 = (tid & 15) * 4; LAS float* tp = tile + q * (64 * 65) + row * 65 + c4;
;                 tp[0] = v[q][j][0]; tp[1] = v[q][j][1]; tp[2] = v[q][j][2]; tp[3] = v[q][j][3]; }
;         __syncthreads();
; #pragma unroll
;         for (int q = 0; q < 4; ++q) { const int it = gi * 4 + q;
;             if (it < total) { const int b = it / per, r = it % per, k0 = (r / tn) * 64, n0 = (r % tn) * 64;
;                 const int n = tid >> 3, kc = (tid & 7) * 8;
;                 if (n0 + n < N) { float f[8];
; #pragma unroll
;                     for (int j = 0; j < 8; ++j) f[j] = tile[q * (64 * 65) + (kc + j) * 65 + n];
;                     u32x4 w; w.x = cvt_pk_bf16(f[0], f[1]); w.y = cvt_pk_bf16(f[2], f[3]); w.z = cvt_pk_bf16(f[4], f[5]); w.w = cvt_pk_bf16(f[6], f[7]);
;                     int nd = n0 + n + nshift; if (nd >= N) nd -= N;
;                     *(u32x4*)(dst + (size_t)b * dbs + (size_t)nd * ldd + kofs + k0 + kc) = w; } } }
; __device__ void phase_convert(const Params& p, LAS unsigned char* lds) {
;     ...
;     cvt_job(tile, p.ewu, (bf16_t*)(ws + WS_WU), NL * NE, 1024, FF, 1024, 0, (size_t)1024 * FF, (size_t)FF * 1024, (int)blockIdx.x, (int)gridDim.x);
.Lcv_ewu_nopf:
	s_waitcnt lgkmcnt(0)
	s_barrier
	ds_read2_b32 v[32:33], v88 offset1:65
	ds_read2_b32 v[34:35], v88 offset0:130 offset1:195
	ds_read2_b32 v[36:37], v89 offset0:4 offset1:69
	ds_read2_b32 v[38:39], v89 offset0:134 offset1:199
	ds_read2_b32 v[40:41], v90 offset1:65
	ds_read2_b32 v[42:43], v90 offset0:130 offset1:195
	ds_read2_b32 v[44:45], v91 offset0:4 offset1:69
	ds_read2_b32 v[46:47], v91 offset0:134 offset1:199
	ds_read2_b32 v[48:49], v92 offset1:65
	ds_read2_b32 v[50:51], v92 offset0:130 offset1:195
	ds_read2_b32 v[52:53], v93 offset0:4 offset1:69
	ds_read2_b32 v[54:55], v93 offset0:134 offset1:199
	ds_read2_b32 v[56:57], v94 offset1:65
	ds_read2_b32 v[58:59], v94 offset0:130 offset1:195
	ds_read2_b32 v[60:61], v95 offset0:4 offset1:69
	ds_read2_b32 v[62:63], v95 offset0:134 offset1:199
	s_waitcnt lgkmcnt(12)
	v_cvt_pk_bf16_f32 v64, v32, v33
	v_cvt_pk_bf16_f32 v65, v34, v35
	v_cvt_pk_bf16_f32 v66, v36, v37
	v_cvt_pk_bf16_f32 v67, v38, v39
	global_store_dwordx4 v103, v[64:67], s[8:9] nt
	s_waitcnt lgkmcnt(8)
	v_cvt_pk_bf16_f32 v68, v40, v41
	v_cvt_pk_bf16_f32 v69, v42, v43
	v_cvt_pk_bf16_f32 v70, v44, v45
	v_cvt_pk_bf16_f32 v71, v46, v47
	s_add_u32 s10, s8, 0x20000
	s_addc_u32 s11, s9, 0
	global_store_dwordx4 v103, v[68:71], s[10:11] nt
	s_waitcnt lgkmcnt(4)
	v_cvt_pk_bf16_f32 v72, v48, v49
	v_cvt_pk_bf16_f32 v73, v50, v51
	v_cvt_pk_bf16_f32 v74, v52, v53
	v_cvt_pk_bf16_f32 v75, v54, v55
	s_add_u32 s10, s8, 0x40000
	s_addc_u32 s11, s9, 0
	global_store_dwordx4 v103, v[72:75], s[10:11] nt
	s_waitcnt lgkmcnt(0)
	v_cvt_pk_bf16_f32 v76, v56, v57
	v_cvt_pk_bf16_f32 v77, v58, v59
	v_cvt_pk_bf16_f32 v78, v60, v61
	v_cvt_pk_bf16_f32 v79, v62, v63
	s_add_u32 s10, s8, 0x60000
	s_addc_u32 s11, s9, 0
	global_store_dwordx4 v103, v[76:79], s[10:11] nt
	s_barrier
	s_mov_b32 s20, s21
	s_cmpk_lt_i32 s20, 0x1000
	s_cbranch_scc1 .Lcv_ewu_loop

; #define LAS __attribute__((address_space(3)))
; __device__ __forceinline__ unsigned cvt_pk_bf16(float lo, float hi) { unsigned r; asm("v_cvt_pk_bf16_f32 %0, %1, %2" : "=v"(r) : "v"(lo), "v"(hi)); return r; }
;     ...
;             for (int j = 0; j < 2; ++j) { const int row = (tid >> 4) + 32 * j, c4 = (tid & 15) * 4; LAS float* tp = tile + q * (64 * 65) + row * 65 + c4;
;                 tp[0] = v[q][j][0]; tp[1] = v[q][j][1]; tp[2] = v[q][j][2]; tp[3] = v[q][j][3]; }
;         __syncthreads();
; #pragma unroll
;         for (int q = 0; q < 4; ++q) { const int it = gi * 4 + q;
;             if (it < total) { const int b = it / per, r = it % per, k0 = (r / tn) * 64, n0 = (r % tn) * 64;
;                 const int n = tid >> 3, kc = (tid & 7) * 8;
;                 if (n0 + n < N) { float f[8];
; #pragma unroll
;                     for (int j = 0; j < 8; ++j) f[j] = tile[q * (64 * 65) + (kc + j) * 65 + n];
;                     u32x4 w; w.x = cvt_pk_bf16(f[0], f[1]); w.y = cvt_pk_bf16(f[2], f[3]); w.z = cvt_pk_bf16(f[4], f[5]); w.w = cvt_pk_bf16(f[6], f[7]);
;                     int nd = n0 + n + nshift; if (nd >= N) nd -= N;
;                     *(u32x4*)(dst + (size_t)b * dbs + (size_t)nd * ldd + kofs + k0 + kc) = w; } } }
; __device__ void phase_convert(const Params& p, LAS unsigned char* lds) {
;     ...
;     cvt_job(tile, p.ewd, (bf16_t*)(ws + WS_WD), NE, FF, 1024, FF, 0, (size_t)FF * 1024, (size_t)1024 * FF, (int)blockIdx.x, (int)gridDim.x);
.Lcv_ewd_nopf:
	s_waitcnt lgkmcnt(0)
	s_barrier
	ds_read2_b32 v[32:33], v88 offset1:65
	ds_read2_b32 v[34:35], v88 offset0:130 offset1:195
	ds_read2_b32 v[36:37], v89 offset0:4 offset1:69
	ds_read2_b32 v[38:39], v89 offset0:134 offset1:199
	ds_read2_b32 v[40:41], v90 offset1:65
	ds_read2_b32 v[42:43], v90 offset0:130 offset1:195
	ds_read2_b32 v[44:45], v91 offset0:4 offset1:69
	ds_read2_b32 v[46:47], v91 offset0:134 offset1:199
	ds_read2_b32 v[48:49], v92 offset1:65
	ds_read2_b32 v[50:51], v92 offset0:130 offset1:195
	ds_read2_b32 v[52:53], v93 offset0:4 offset1:69
	ds_read2_b32 v[54:55], v93 offset0:134 offset1:199
	ds_read2_b32 v[56:57], v94 offset1:65
	ds_read2_b32 v[58:59], v94 offset0:130 offset1:195
	ds_read2_b32 v[60:61], v95 offset0:4 offset1:69
	ds_read2_b32 v[62:63], v95 offset0:134 offset1:199
	s_waitcnt lgkmcnt(12)
	v_cvt_pk_bf16_f32 v64, v32, v33
	v_cvt_pk_bf16_f32 v65, v34, v35
	v_cvt_pk_bf16_f32 v66, v36, v37
	v_cvt_pk_bf16_f32 v67, v38, v39
	global_store_dwordx4 v103, v[64:67], s[8:9] nt
	s_waitcnt lgkmcnt(8)
	v_cvt_pk_bf16_f32 v68, v40, v41
	v_cvt_pk_bf16_f32 v69, v42, v43
	v_cvt_pk_bf16_f32 v70, v44, v45
	v_cvt_pk_bf16_f32 v71, v46, v47
	s_add_u32 s10, s8, 0x40000
	s_addc_u32 s11, s9, 0
	global_store_dwordx4 v103, v[68:71], s[10:11] nt
	s_waitcnt lgkmcnt(4)
	v_cvt_pk_bf16_f32 v72, v48, v49
	v_cvt_pk_bf16_f32 v73, v50, v51
	v_cvt_pk_bf16_f32 v74, v52, v53
	v_cvt_pk_bf16_f32 v75, v54, v55
	s_add_u32 s10, s8, 0x80000
	s_addc_u32 s11, s9, 0
	global_store_dwordx4 v103, v[72:75], s[10:11] nt
	s_waitcnt lgkmcnt(0)
	v_cvt_pk_bf16_f32 v76, v56, v57
	v_cvt_pk_bf16_f32 v77, v58, v59
	v_cvt_pk_bf16_f32 v78, v60, v61
	v_cvt_pk_bf16_f32 v79, v62, v63
	s_add_u32 s10, s8, 0xc0000
	s_addc_u32 s11, s9, 0
	global_store_dwordx4 v103, v[76:79], s[10:11] nt
	s_barrier
	s_mov_b32 s20, s21
	s_cmpk_lt_i32 s20, 0x800
	s_cbranch_scc1 .Lcv_ewd_loop
